# v46 + GEMM K loops (in-proj, gate/up, down): first body peeled with C=0 MFMAs, per-tile accumulator clears removed
# baseline (speedup 1.0000x reference)
; #define PG8_STAGE(bufoff, gbase, voff) do { _Pragma("unroll") for (int _i = 0; _i < 2; ++_i) \
;         __builtin_amdgcn_global_load_lds((const unsigned*)((const char*)(gbase) + (voff)[_i]), (PG8_LAS unsigned*)(lds + (bufoff) + ldsw + _i * 8192), 16, 0, 0); } while (0)
; #define PG8_WAIT_V(n) asm volatile("s_waitcnt vmcnt(" #n ")" ::: "memory")
; template <class Epi, class Sched, bool ALIGN_EPI = false, bool SP2 = false, bool F16 = false>
; __device__ __forceinline__ void gemm_phase(PG8_LAS unsigned char* lds, const Gemm g, const Sched& S, const Epi& E) {
;     ...
;         const bool has_next = S.next(ui + 1, nxt);
;         const char* nA = has_next ? (const char*)g.A + (size_t)nxt.pm * tstep : cA; const char* nB = has_next ? (const char*)g.Bt + (size_t)nxt.pn * tstep + (nxt.pm >= g.mhalf ? g.bstride : (size_t)0) : cB;
;         for (int t = 0; t < nt; t += 2) {
;             if constexpr (Epi::KHOOK) { if (t == 4 || t == 10) E.khook(acc, cur, t, wr, fr); }
;             const bool last = (t == nt - 2);
;             const char* a1 = cA + (size_t)(t + 1) * kstep;
;             const char* a2 = last ? nA : cA + (size_t)(t + 2) * kstep; const char* b2 = last ? nB : cB + (size_t)(t + 2) * kstep;
;             const char* a3 = a2 + kstep; const char* b3 = b2 + kstep;
;             if (last && has_next) S.a_ready(nxt);
;             if constexpr (SP2) {
;             PG8_LDB(B0, 0, 0); PG8_LDB(B1, 0, 1); PG8_SCHED; PG8_LDA(At, 0, 0); PG8_STAGE(PG8_SA(1, 1), a1 + hstep, voffA);
;             PG8_WAIT_V(8); PG8_WAIT_L(0); PG8_BAR; PG8_MMA(0, 0, At, B0); PG8_MMA(0, 1, At, B1); PG8_BAR; PG8_SCHED;
;             PG8_LDA(At, 0, 1); PG8_STAGE(PG8_SB(0, 0), b2, voffB); PG8_STAGE(PG8_SB(0, 1), b2 + hstep, voffB); PG8_STAGE(PG8_SA(0, 0), a2, voffA);
;             PG8_WAIT_V(8); PG8_WAIT_L(0); PG8_BAR; PG8_MMA(1, 0, At, B0); PG8_MMA(1, 1, At, B1); PG8_BAR; PG8_SCHED;
;             PG8_LDB(B0, 1, 0); PG8_LDB(B1, 1, 1); PG8_SCHED; PG8_LDA(At, 1, 0); PG8_STAGE(PG8_SA(0, 1), a2 + hstep, voffA);
;             PG8_WAIT_V(8); PG8_WAIT_L(0); PG8_BAR; PG8_MMA(0, 0, At, B0); PG8_MMA(0, 1, At, B1); PG8_BAR; PG8_SCHED;
;             PG8_LDA(At, 1, 1); PG8_STAGE(PG8_SB(1, 0), b3, voffB); PG8_STAGE(PG8_SB(1, 1), b3 + hstep, voffB); PG8_STAGE(PG8_SA(1, 0), a3, voffA);
;             PG8_WAIT_V(8); PG8_WAIT_L(0); PG8_BAR; PG8_MMA(1, 0, At, B0); PG8_MMA(1, 1, At, B1); PG8_BAR; PG8_SCHED;
.LBB0_255:
	s_ashr_i32 s29, s28, 31
	s_lshl_b64 s[4:5], s[28:29], 19
	s_add_u32 s46, s96, s4
	s_addc_u32 s47, s97, s5
	s_and_b64 s[4:5], s[40:41], exec
	s_cselect_b32 s4, s47, s1
	s_cselect_b32 s5, s46, s0
	s_ashr_i32 s73, s72, 31
	s_lshl_b64 s[54:55], s[72:73], 19
	s_add_u32 s7, s30, s54
	s_addc_u32 s34, s31, s55
	s_cmp_gt_i32 s28, 63
	s_cselect_b32 s54, 0x400000, 0
	s_add_u32 s64, s7, s54
	s_addc_u32 s65, s34, 0
	s_and_b64 s[54:55], s[40:41], exec
	s_cselect_b32 s7, s65, s43
	s_cselect_b32 s34, s64, s42
	s_add_u32 s0, s0, 0x40080
	s_addc_u32 s1, s1, 0
	s_add_u32 s59, s42, 0x100
	s_addc_u32 s61, s43, 0
	s_mov_b32 s67, -2
	s_waitcnt vmcnt(0)
	v_add_u32_e32 v242, 0x10000, v239
	s_add_u32 s42, s0, 0xfffc0080
	s_addc_u32 s43, s1, -1
	s_add_i32 s68, 0, 0x10000
	s_cmp_eq_u32 s67, 12
	s_cselect_b32 s55, s4, s43
	s_cselect_b32 s54, s5, s42
	s_cselect_b32 s43, s7, s61
	s_cselect_b32 s42, s34, s59
	s_add_i32 s70, 0, 0x14000
	ds_read_b128 v[130:133], v242
	ds_read_b128 v[134:137], v242 offset:1024
	ds_read_b128 v[138:141], v242 offset:2048
	ds_read_b128 v[162:165], v242 offset:3072
	ds_read_b128 v[166:169], v242 offset:16384
	ds_read_b128 v[170:173], v242 offset:17408
	ds_read_b128 v[186:189], v242 offset:18432
	ds_read_b128 v[190:193], v242 offset:19456
	s_add_i32 m0, s21, 0xc000
	ds_read_b128 v[194:197], v240
	ds_read_b128 v[198:201], v240 offset:1024
	ds_read_b128 v[202:205], v240 offset:2048
	ds_read_b128 v[206:209], v240 offset:3072
	ds_read_b128 v[210:213], v240 offset:4096
	ds_read_b128 v[214:217], v240 offset:5120
	ds_read_b128 v[218:221], v240 offset:6144
	ds_read_b128 v[222:225], v240 offset:7168
	global_load_lds_dwordx4 v154, s[0:1]
	s_add_i32 m0, s21, 0xe000
	s_nop 0
	global_load_lds_dwordx4 v156, s[0:1]
	s_waitcnt vmcnt(8)
	s_waitcnt lgkmcnt(0)
	s_barrier
	s_setprio 1
	s_waitcnt lgkmcnt(0)
	v_mfma_f32_16x16x32_f16 v[124:127], v[130:133], v[194:197], 0
	v_mfma_f32_16x16x32_f16 v[120:123], v[138:141], v[194:197], 0
	v_mfma_f32_16x16x32_f16 v[116:119], v[130:133], v[202:205], 0
	v_mfma_f32_16x16x32_f16 v[112:115], v[138:141], v[202:205], 0
	v_mfma_f32_16x16x32_f16 v[108:111], v[130:133], v[210:213], 0
	v_mfma_f32_16x16x32_f16 v[104:107], v[138:141], v[210:213], 0
	v_mfma_f32_16x16x32_f16 v[100:103], v[130:133], v[218:221], 0
	v_mfma_f32_16x16x32_f16 v[96:99], v[138:141], v[218:221], 0
	v_mfma_f32_16x16x32_f16 v[124:127], v[134:137], v[198:201], v[124:127]
	v_mfma_f32_16x16x32_f16 v[120:123], v[162:165], v[198:201], v[120:123]
	v_mfma_f32_16x16x32_f16 v[116:119], v[134:137], v[206:209], v[116:119]
	v_mfma_f32_16x16x32_f16 v[112:115], v[162:165], v[206:209], v[112:115]
	v_mfma_f32_16x16x32_f16 v[108:111], v[134:137], v[214:217], v[108:111]
	v_mfma_f32_16x16x32_f16 v[104:107], v[162:165], v[214:217], v[104:107]
	v_mfma_f32_16x16x32_f16 v[100:103], v[134:137], v[222:225], v[100:103]
	v_mfma_f32_16x16x32_f16 v[96:99], v[162:165], v[222:225], v[96:99]
	v_mfma_f32_16x16x32_f16 v[60:63], v[166:169], v[194:197], 0
	v_mfma_f32_16x16x32_f16 v[56:59], v[186:189], v[194:197], 0
	v_mfma_f32_16x16x32_f16 v[52:55], v[166:169], v[202:205], 0
	v_mfma_f32_16x16x32_f16 v[48:51], v[186:189], v[202:205], 0
	v_mfma_f32_16x16x32_f16 v[44:47], v[166:169], v[210:213], 0
	v_mfma_f32_16x16x32_f16 v[40:43], v[186:189], v[210:213], 0
	v_mfma_f32_16x16x32_f16 v[36:39], v[166:169], v[218:221], 0
	v_mfma_f32_16x16x32_f16 v[32:35], v[186:189], v[218:221], 0
	v_mfma_f32_16x16x32_f16 v[60:63], v[170:173], v[198:201], v[60:63]
	v_mfma_f32_16x16x32_f16 v[56:59], v[190:193], v[198:201], v[56:59]
	v_mfma_f32_16x16x32_f16 v[52:55], v[170:173], v[206:209], v[52:55]
	v_mfma_f32_16x16x32_f16 v[48:51], v[190:193], v[206:209], v[48:51]
	v_mfma_f32_16x16x32_f16 v[44:47], v[170:173], v[214:217], v[44:47]
	v_mfma_f32_16x16x32_f16 v[40:43], v[190:193], v[214:217], v[40:43]
	v_mfma_f32_16x16x32_f16 v[36:39], v[170:173], v[222:225], v[36:39]
	v_mfma_f32_16x16x32_f16 v[32:35], v[190:193], v[222:225], v[32:35]
	s_setprio 0
	s_barrier
	s_add_u32 s98, s42, s16
	s_addc_u32 s99, s43, s17
	s_add_u32 s100, s54, s16
	s_addc_u32 s101, s55, s17
	s_add_i32 s68, s68, s20
	s_mov_b32 m0, s68
	ds_read_b128 v[194:197], v240 offset:16384
	ds_read_b128 v[198:201], v240 offset:17408
	ds_read_b128 v[202:205], v240 offset:18432
	ds_read_b128 v[206:209], v240 offset:19456
	ds_read_b128 v[210:213], v240 offset:20480
	ds_read_b128 v[214:217], v240 offset:21504
	ds_read_b128 v[218:221], v240 offset:22528
	ds_read_b128 v[222:225], v240 offset:23552
	global_load_lds_dwordx4 v146, s[42:43]
	s_add_i32 m0, s68, 0x2000
	s_add_u32 s68, s42, 0x40000
	s_addc_u32 s69, s43, 0
	s_add_i32 s70, s70, s20
	global_load_lds_dwordx4 v142, s[42:43]
	s_mov_b32 m0, s70
	s_nop 0
	global_load_lds_dwordx4 v146, s[68:69]
	s_add_i32 m0, s70, 0x2000
	s_nop 0
	global_load_lds_dwordx4 v142, s[68:69]
	s_mov_b32 m0, s21
	s_nop 0
	global_load_lds_dwordx4 v148, s[54:55]
	s_mov_b32 m0, s14
	s_nop 0
	global_load_lds_dwordx4 v144, s[54:55]
	s_waitcnt vmcnt(8)
	s_waitcnt lgkmcnt(0)
	s_barrier
; #define PG8_STAGE(bufoff, gbase, voff) do { _Pragma("unroll") for (int _i = 0; _i < 2; ++_i) \
;         __builtin_amdgcn_global_load_lds((const unsigned*)((const char*)(gbase) + (voff)[_i]), (PG8_LAS unsigned*)(lds + (bufoff) + ldsw + _i * 8192), 16, 0, 0); } while (0)
; #define PG8_LDA(dst, b, h) do { _Pragma("unroll") for (int m = 0; m < 4; ++m) _Pragma("unroll") for (int k = 0; k < 2; ++k) dst[m][k] = *(const PG8_LAS bf16x8*)(lds + PG8_SA(b, h) + aoff + m * 2048 + k * 1024); } while (0)
; #define PG8_LDB(dst, b, h) do { _Pragma("unroll") for (int n = 0; n < 2; ++n) _Pragma("unroll") for (int k = 0; k < 2; ++k) dst[n][k] = *(const PG8_LAS bf16x8*)(lds + PG8_SB(b, h) + boff + n * 2048 + k * 1024); } while (0)
; #define PG8_MMA(ai, bj, At, Bt) do { __builtin_amdgcn_s_setprio(1); _Pragma("unroll") for (int m = 0; m < 4; ++m) _Pragma("unroll") for (int n = 0; n < 2; ++n) _Pragma("unroll") for (int k = 0; k < 2; ++k) \
;         acc[ai][bj][m][n] = mma16<F16>(Bt[n][k], At[m][k], acc[ai][bj][m][n]); __builtin_amdgcn_s_setprio(0); } while (0)
; #define PG8_WAIT_V(n) asm volatile("s_waitcnt vmcnt(" #n ")" ::: "memory")
; #define PG8_WAIT_L(n) asm volatile("s_waitcnt lgkmcnt(" #n ")" ::: "memory")
; #define PG8_BAR __builtin_amdgcn_s_barrier()
; #define PG8_SCHED __builtin_amdgcn_sched_barrier(0)
; template <class Epi, class Sched, bool ALIGN_EPI = false, bool SP2 = false, bool F16 = false>
; __device__ __forceinline__ void gemm_phase(PG8_LAS unsigned char* lds, const Gemm g, const Sched& S, const Epi& E) {
;     ...
;             PG8_WAIT_V(8); PG8_WAIT_L(0); PG8_BAR; PG8_MMA(1, 0, At, B0); PG8_MMA(1, 1, At, B1); PG8_BAR; PG8_SCHED;
;             PG8_LDB(B0, 1, 0); PG8_LDB(B1, 1, 1); PG8_SCHED; PG8_LDA(At, 1, 0); PG8_STAGE(PG8_SA(0, 1), a2 + hstep, voffA);
;             PG8_WAIT_V(8); PG8_WAIT_L(0); PG8_BAR; PG8_MMA(0, 0, At, B0); PG8_MMA(0, 1, At, B1); PG8_BAR; PG8_SCHED;
	s_setprio 1
	s_waitcnt lgkmcnt(0)
	v_mfma_f32_16x16x32_f16 v[92:95], v[130:133], v[194:197], 0
	v_mfma_f32_16x16x32_f16 v[88:91], v[138:141], v[194:197], 0
	v_mfma_f32_16x16x32_f16 v[84:87], v[130:133], v[202:205], 0
	v_mfma_f32_16x16x32_f16 v[80:83], v[138:141], v[202:205], 0
	v_mfma_f32_16x16x32_f16 v[76:79], v[130:133], v[210:213], 0
	v_mfma_f32_16x16x32_f16 v[72:75], v[138:141], v[210:213], 0
	v_mfma_f32_16x16x32_f16 v[68:71], v[130:133], v[218:221], 0
	v_mfma_f32_16x16x32_f16 v[64:67], v[138:141], v[218:221], 0
	v_mfma_f32_16x16x32_f16 v[92:95], v[134:137], v[198:201], v[92:95]
	v_mfma_f32_16x16x32_f16 v[88:91], v[162:165], v[198:201], v[88:91]
	v_mfma_f32_16x16x32_f16 v[84:87], v[134:137], v[206:209], v[84:87]
	v_mfma_f32_16x16x32_f16 v[80:83], v[162:165], v[206:209], v[80:83]
	v_mfma_f32_16x16x32_f16 v[76:79], v[134:137], v[214:217], v[76:79]
	v_mfma_f32_16x16x32_f16 v[72:75], v[162:165], v[214:217], v[72:75]
	v_mfma_f32_16x16x32_f16 v[68:71], v[134:137], v[222:225], v[68:71]
	v_mfma_f32_16x16x32_f16 v[64:67], v[162:165], v[222:225], v[64:67]
	v_mfma_f32_16x16x32_f16 v[28:31], v[166:169], v[194:197], 0
	v_mfma_f32_16x16x32_f16 v[24:27], v[186:189], v[194:197], 0
	v_mfma_f32_16x16x32_f16 v[20:23], v[166:169], v[202:205], 0
	v_mfma_f32_16x16x32_f16 v[16:19], v[186:189], v[202:205], 0
	v_mfma_f32_16x16x32_f16 v[12:15], v[166:169], v[210:213], 0
	v_mfma_f32_16x16x32_f16 v[8:11], v[186:189], v[210:213], 0
	v_mfma_f32_16x16x32_f16 v[4:7], v[166:169], v[218:221], 0
	v_mfma_f32_16x16x32_f16 v[0:3], v[186:189], v[218:221], 0
	v_mfma_f32_16x16x32_f16 v[28:31], v[170:173], v[198:201], v[28:31]
	v_mfma_f32_16x16x32_f16 v[24:27], v[190:193], v[198:201], v[24:27]
	v_mfma_f32_16x16x32_f16 v[20:23], v[170:173], v[206:209], v[20:23]
	v_mfma_f32_16x16x32_f16 v[16:19], v[190:193], v[206:209], v[16:19]
	v_mfma_f32_16x16x32_f16 v[12:15], v[170:173], v[214:217], v[12:15]
	v_mfma_f32_16x16x32_f16 v[8:11], v[190:193], v[214:217], v[8:11]
	v_mfma_f32_16x16x32_f16 v[4:7], v[170:173], v[222:225], v[4:7]
	v_mfma_f32_16x16x32_f16 v[0:3], v[190:193], v[222:225], v[0:3]
	s_setprio 0
	s_barrier
	s_add_i32 s68, 0, 0x18000
	s_add_i32 s69, 0, 0x1c000
	ds_read_b128 v[130:133], v242 offset:32768
	ds_read_b128 v[134:137], v242 offset:33792
	ds_read_b128 v[138:141], v242 offset:34816
	ds_read_b128 v[162:165], v242 offset:35840
	ds_read_b128 v[166:169], v242 offset:49152
	ds_read_b128 v[170:173], v242 offset:50176
	ds_read_b128 v[186:189], v242 offset:51200
	ds_read_b128 v[190:193], v242 offset:52224
	s_add_u32 s54, s54, 0x40000
	s_addc_u32 s55, s55, 0
	s_mov_b32 m0, s15
	ds_read_b128 v[194:197], v240 offset:32768
	ds_read_b128 v[198:201], v240 offset:33792
	ds_read_b128 v[202:205], v240 offset:34816
	ds_read_b128 v[206:209], v240 offset:35840
	ds_read_b128 v[210:213], v240 offset:36864
	ds_read_b128 v[214:217], v240 offset:37888
	ds_read_b128 v[218:221], v240 offset:38912
	ds_read_b128 v[222:225], v240 offset:39936
	global_load_lds_dwordx4 v148, s[54:55]
	s_mov_b32 m0, s37
	s_nop 0
	global_load_lds_dwordx4 v144, s[54:55]
	s_waitcnt vmcnt(8)
	s_waitcnt lgkmcnt(0)
	s_barrier
	s_setprio 1
	s_waitcnt lgkmcnt(0)
	v_mfma_f32_16x16x32_f16 v[124:127], v[130:133], v[194:197], v[124:127]
	v_mfma_f32_16x16x32_f16 v[120:123], v[138:141], v[194:197], v[120:123]
	v_mfma_f32_16x16x32_f16 v[116:119], v[130:133], v[202:205], v[116:119]
	v_mfma_f32_16x16x32_f16 v[112:115], v[138:141], v[202:205], v[112:115]
	v_mfma_f32_16x16x32_f16 v[108:111], v[130:133], v[210:213], v[108:111]
	v_mfma_f32_16x16x32_f16 v[104:107], v[138:141], v[210:213], v[104:107]
	v_mfma_f32_16x16x32_f16 v[100:103], v[130:133], v[218:221], v[100:103]
	v_mfma_f32_16x16x32_f16 v[96:99], v[138:141], v[218:221], v[96:99]
	v_mfma_f32_16x16x32_f16 v[124:127], v[134:137], v[198:201], v[124:127]
	v_mfma_f32_16x16x32_f16 v[120:123], v[162:165], v[198:201], v[120:123]
	v_mfma_f32_16x16x32_f16 v[116:119], v[134:137], v[206:209], v[116:119]
	v_mfma_f32_16x16x32_f16 v[112:115], v[162:165], v[206:209], v[112:115]
	v_mfma_f32_16x16x32_f16 v[108:111], v[134:137], v[214:217], v[108:111]
	v_mfma_f32_16x16x32_f16 v[104:107], v[162:165], v[214:217], v[104:107]
	v_mfma_f32_16x16x32_f16 v[100:103], v[134:137], v[222:225], v[100:103]
	v_mfma_f32_16x16x32_f16 v[96:99], v[162:165], v[222:225], v[96:99]
	v_mfma_f32_16x16x32_f16 v[60:63], v[166:169], v[194:197], v[60:63]
	v_mfma_f32_16x16x32_f16 v[56:59], v[186:189], v[194:197], v[56:59]
	v_mfma_f32_16x16x32_f16 v[52:55], v[166:169], v[202:205], v[52:55]
	v_mfma_f32_16x16x32_f16 v[48:51], v[186:189], v[202:205], v[48:51]
	v_mfma_f32_16x16x32_f16 v[44:47], v[166:169], v[210:213], v[44:47]
	v_mfma_f32_16x16x32_f16 v[40:43], v[186:189], v[210:213], v[40:43]
	v_mfma_f32_16x16x32_f16 v[36:39], v[166:169], v[218:221], v[36:39]
	v_mfma_f32_16x16x32_f16 v[32:35], v[186:189], v[218:221], v[32:35]
	v_mfma_f32_16x16x32_f16 v[60:63], v[170:173], v[198:201], v[60:63]
	v_mfma_f32_16x16x32_f16 v[56:59], v[190:193], v[198:201], v[56:59]
	v_mfma_f32_16x16x32_f16 v[52:55], v[170:173], v[206:209], v[52:55]
	v_mfma_f32_16x16x32_f16 v[48:51], v[190:193], v[206:209], v[48:51]
	v_mfma_f32_16x16x32_f16 v[44:47], v[170:173], v[214:217], v[44:47]
	v_mfma_f32_16x16x32_f16 v[40:43], v[190:193], v[214:217], v[40:43]
	v_mfma_f32_16x16x32_f16 v[36:39], v[170:173], v[222:225], v[36:39]
	v_mfma_f32_16x16x32_f16 v[32:35], v[190:193], v[222:225], v[32:35]
	s_setprio 0
	s_barrier
; #define PG8_STAGE(bufoff, gbase, voff) do { _Pragma("unroll") for (int _i = 0; _i < 2; ++_i) \
;         __builtin_amdgcn_global_load_lds((const unsigned*)((const char*)(gbase) + (voff)[_i]), (PG8_LAS unsigned*)(lds + (bufoff) + ldsw + _i * 8192), 16, 0, 0); } while (0)
; #define PG8_LDA(dst, b, h) do { _Pragma("unroll") for (int m = 0; m < 4; ++m) _Pragma("unroll") for (int k = 0; k < 2; ++k) dst[m][k] = *(const PG8_LAS bf16x8*)(lds + PG8_SA(b, h) + aoff + m * 2048 + k * 1024); } while (0)
; #define PG8_MMA(ai, bj, At, Bt) do { __builtin_amdgcn_s_setprio(1); _Pragma("unroll") for (int m = 0; m < 4; ++m) _Pragma("unroll") for (int n = 0; n < 2; ++n) _Pragma("unroll") for (int k = 0; k < 2; ++k) \
;         acc[ai][bj][m][n] = mma16<F16>(Bt[n][k], At[m][k], acc[ai][bj][m][n]); __builtin_amdgcn_s_setprio(0); } while (0)
; #define PG8_WAIT_V(n) asm volatile("s_waitcnt vmcnt(" #n ")" ::: "memory")
; #define PG8_WAIT_L(n) asm volatile("s_waitcnt lgkmcnt(" #n ")" ::: "memory")
; #define PG8_BAR __builtin_amdgcn_s_barrier()
; #define PG8_SCHED __builtin_amdgcn_sched_barrier(0)
; template <class Epi, class Sched, bool ALIGN_EPI = false, bool SP2 = false, bool F16 = false>
; __device__ __forceinline__ void gemm_phase(PG8_LAS unsigned char* lds, const Gemm g, const Sched& S, const Epi& E) {
;     ...
;         for (int t = 0; t < nt; t += 2) {
;     ...
;             PG8_LDA(At, 1, 1); PG8_STAGE(PG8_SB(1, 0), b3, voffB); PG8_STAGE(PG8_SB(1, 1), b3 + hstep, voffB); PG8_STAGE(PG8_SA(1, 0), a3, voffA);
;             PG8_WAIT_V(8); PG8_WAIT_L(0); PG8_BAR; PG8_MMA(1, 0, At, B0); PG8_MMA(1, 1, At, B1); PG8_BAR; PG8_SCHED;
	s_add_i32 s54, s68, s20
	s_mov_b32 m0, s54
	ds_read_b128 v[194:197], v240 offset:49152
	ds_read_b128 v[198:201], v240 offset:50176
	ds_read_b128 v[202:205], v240 offset:51200
	ds_read_b128 v[206:209], v240 offset:52224
	ds_read_b128 v[210:213], v240 offset:53248
	ds_read_b128 v[214:217], v240 offset:54272
	ds_read_b128 v[218:221], v240 offset:55296
	ds_read_b128 v[222:225], v240 offset:56320
	global_load_lds_dwordx4 v146, s[98:99]
	s_add_i32 m0, s54, 0x2000
	s_add_u32 s42, s42, 0x40080
	s_addc_u32 s43, s43, 0
	s_add_i32 s54, s69, s20
	global_load_lds_dwordx4 v142, s[98:99]
	s_mov_b32 m0, s54
	s_nop 0
	global_load_lds_dwordx4 v146, s[42:43]
	s_add_i32 m0, s54, 0x2000
	s_nop 0
	global_load_lds_dwordx4 v142, s[42:43]
	s_mov_b32 m0, s44
	s_nop 0
	global_load_lds_dwordx4 v148, s[100:101]
	s_mov_b32 m0, s45
	s_nop 0
	global_load_lds_dwordx4 v144, s[100:101]
	s_waitcnt vmcnt(8)
	s_waitcnt lgkmcnt(0)
	s_barrier
	s_setprio 1
	s_waitcnt lgkmcnt(0)
	v_mfma_f32_16x16x32_f16 v[92:95], v[130:133], v[194:197], v[92:95]
	v_mfma_f32_16x16x32_f16 v[88:91], v[138:141], v[194:197], v[88:91]
	v_mfma_f32_16x16x32_f16 v[84:87], v[130:133], v[202:205], v[84:87]
	v_mfma_f32_16x16x32_f16 v[80:83], v[138:141], v[202:205], v[80:83]
	v_mfma_f32_16x16x32_f16 v[76:79], v[130:133], v[210:213], v[76:79]
	v_mfma_f32_16x16x32_f16 v[72:75], v[138:141], v[210:213], v[72:75]
	v_mfma_f32_16x16x32_f16 v[68:71], v[130:133], v[218:221], v[68:71]
	v_mfma_f32_16x16x32_f16 v[64:67], v[138:141], v[218:221], v[64:67]
	v_mfma_f32_16x16x32_f16 v[92:95], v[134:137], v[198:201], v[92:95]
	v_mfma_f32_16x16x32_f16 v[88:91], v[162:165], v[198:201], v[88:91]
	v_mfma_f32_16x16x32_f16 v[84:87], v[134:137], v[206:209], v[84:87]
	v_mfma_f32_16x16x32_f16 v[80:83], v[162:165], v[206:209], v[80:83]
	v_mfma_f32_16x16x32_f16 v[76:79], v[134:137], v[214:217], v[76:79]
	v_mfma_f32_16x16x32_f16 v[72:75], v[162:165], v[214:217], v[72:75]
	v_mfma_f32_16x16x32_f16 v[68:71], v[134:137], v[222:225], v[68:71]
	v_mfma_f32_16x16x32_f16 v[64:67], v[162:165], v[222:225], v[64:67]
	v_mfma_f32_16x16x32_f16 v[28:31], v[166:169], v[194:197], v[28:31]
	v_mfma_f32_16x16x32_f16 v[24:27], v[186:189], v[194:197], v[24:27]
	v_mfma_f32_16x16x32_f16 v[20:23], v[166:169], v[202:205], v[20:23]
	v_mfma_f32_16x16x32_f16 v[16:19], v[186:189], v[202:205], v[16:19]
	v_mfma_f32_16x16x32_f16 v[12:15], v[166:169], v[210:213], v[12:15]
	v_mfma_f32_16x16x32_f16 v[8:11], v[186:189], v[210:213], v[8:11]
	v_mfma_f32_16x16x32_f16 v[4:7], v[166:169], v[218:221], v[4:7]
	v_mfma_f32_16x16x32_f16 v[0:3], v[186:189], v[218:221], v[0:3]
	v_mfma_f32_16x16x32_f16 v[28:31], v[170:173], v[198:201], v[28:31]
	v_mfma_f32_16x16x32_f16 v[24:27], v[190:193], v[198:201], v[24:27]
	v_mfma_f32_16x16x32_f16 v[20:23], v[170:173], v[206:209], v[20:23]
	v_mfma_f32_16x16x32_f16 v[16:19], v[190:193], v[206:209], v[16:19]
	v_mfma_f32_16x16x32_f16 v[12:15], v[170:173], v[214:217], v[12:15]
	v_mfma_f32_16x16x32_f16 v[8:11], v[190:193], v[214:217], v[8:11]
	v_mfma_f32_16x16x32_f16 v[4:7], v[170:173], v[222:225], v[4:7]
	v_mfma_f32_16x16x32_f16 v[0:3], v[190:193], v[222:225], v[0:3]
	s_setprio 0
	s_barrier
	s_add_i32 s67, s67, 2
	s_add_u32 s0, s0, 0x100
	s_addc_u32 s1, s1, 0
	s_add_u32 s59, s59, 0x100
	s_addc_u32 s61, s61, 0
	s_cmp_gt_u32 s67, 13

; #define PG8_STAGE(bufoff, gbase, voff) do { _Pragma("unroll") for (int _i = 0; _i < 2; ++_i) \
;         __builtin_amdgcn_global_load_lds((const unsigned*)((const char*)(gbase) + (voff)[_i]), (PG8_LAS unsigned*)(lds + (bufoff) + ldsw + _i * 8192), 16, 0, 0); } while (0)
; #define PG8_LDA(dst, b, h) do { _Pragma("unroll") for (int m = 0; m < 4; ++m) _Pragma("unroll") for (int k = 0; k < 2; ++k) dst[m][k] = *(const PG8_LAS bf16x8*)(lds + PG8_SA(b, h) + aoff + m * 2048 + k * 1024); } while (0)
; #define PG8_LDB(dst, b, h) do { _Pragma("unroll") for (int n = 0; n < 2; ++n) _Pragma("unroll") for (int k = 0; k < 2; ++k) dst[n][k] = *(const PG8_LAS bf16x8*)(lds + PG8_SB(b, h) + boff + n * 2048 + k * 1024); } while (0)
; #define PG8_MMA(ai, bj, At, Bt) do { __builtin_amdgcn_s_setprio(1); _Pragma("unroll") for (int m = 0; m < 4; ++m) _Pragma("unroll") for (int n = 0; n < 2; ++n) _Pragma("unroll") for (int k = 0; k < 2; ++k) \
;         acc[ai][bj][m][n] = mma16<F16>(Bt[n][k], At[m][k], acc[ai][bj][m][n]); __builtin_amdgcn_s_setprio(0); } while (0)
; #define PG8_WAIT_V(n) asm volatile("s_waitcnt vmcnt(" #n ")" ::: "memory")
; #define PG8_WAIT_L(n) asm volatile("s_waitcnt lgkmcnt(" #n ")" ::: "memory")
; #define PG8_BAR __builtin_amdgcn_s_barrier()
; #define PG8_SCHED __builtin_amdgcn_sched_barrier(0)
; template <class Epi, class Sched, bool ALIGN_EPI = false, bool SP2 = false, bool F16 = false>
; __device__ __forceinline__ void gemm_phase(PG8_LAS unsigned char* lds, const Gemm g, const Sched& S, const Epi& E) {
;     ...
;             PG8_LDB(B0, 0, 0); PG8_LDB(B1, 0, 1); PG8_SCHED; PG8_LDA(At, 0, 0); PG8_STAGE(PG8_SA(1, 1), a1 + hstep, voffA);
;             PG8_WAIT_V(8); PG8_WAIT_L(0); PG8_BAR; PG8_MMA(0, 0, At, B0); PG8_MMA(0, 1, At, B1); PG8_BAR; PG8_SCHED;
;             PG8_LDA(At, 0, 1); PG8_STAGE(PG8_SB(0, 0), b2, voffB); PG8_STAGE(PG8_SB(0, 1), b2 + hstep, voffB); PG8_STAGE(PG8_SA(0, 0), a2, voffA);
;             PG8_WAIT_V(8); PG8_WAIT_L(0); PG8_BAR; PG8_MMA(1, 0, At, B0); PG8_MMA(1, 1, At, B1); PG8_BAR; PG8_SCHED;
;     ...
; #pragma unroll
;         for (int a = 0; a < 2; ++a)
; #pragma unroll
;             for (int b = 0; b < 2; ++b)
; #pragma unroll
;                 for (int m = 0; m < 4; ++m)
; #pragma unroll
;                     for (int n = 0; n < 2; ++n) acc[a][b][m][n] = (f32x4){0.f, 0.f, 0.f, 0.f};
.LBB0_903:
	s_ashr_i32 s49, s48, 31
	s_lshl_b64 s[4:5], s[48:49], 19
	s_add_u32 s50, s96, s4
	s_addc_u32 s51, s97, s5
	s_and_b64 s[4:5], s[40:41], exec
	s_cselect_b32 s4, s51, s55
	s_cselect_b32 s5, s50, s54
	s_ashr_i32 s47, s46, 31
	s_lshl_b64 s[52:53], s[46:47], 19
	s_add_u32 s37, s6, s52
	s_addc_u32 s47, s7, s53
	s_cmp_gt_i32 s48, 63
	s_cselect_b32 s49, 0xb00000, 0
	s_add_u32 s52, s37, s49
	s_addc_u32 s53, s47, 0
	s_and_b64 s[58:59], s[40:41], exec
	s_cselect_b32 s37, s53, s57
	s_cselect_b32 s47, s52, s56
	s_add_u32 s54, s54, 0x40080
	s_addc_u32 s55, s55, 0
	s_add_u32 s49, s56, 0x100
	s_addc_u32 s60, s57, 0
	s_mov_b32 s61, -2
	s_waitcnt vmcnt(0)
	v_add_u32_e32 v172, 0x10000, v163
	s_add_u32 s56, s54, 0xfffc0080
	s_addc_u32 s57, s55, -1
	s_add_i32 s62, 0, 0x10000
	s_cmp_eq_u32 s61, 12
	s_cselect_b32 s59, s4, s57
	s_cselect_b32 s58, s5, s56
	s_cselect_b32 s57, s37, s60
	s_cselect_b32 s56, s47, s49
	s_add_i32 s64, 0, 0x14000
	ds_read_b128 v[32:35], v172
	ds_read_b128 v[36:39], v172 offset:1024
	ds_read_b128 v[40:43], v172 offset:2048
	ds_read_b128 v[44:47], v172 offset:3072
	ds_read_b128 v[156:159], v172 offset:16384
	ds_read_b128 v[168:171], v172 offset:17408
	ds_read_b128 v[186:189], v172 offset:18432
	ds_read_b128 v[190:193], v172 offset:19456
	s_add_i32 m0, s9, 0xc000
	ds_read_b128 v[194:197], v165
	ds_read_b128 v[198:201], v165 offset:1024
	ds_read_b128 v[202:205], v165 offset:2048
	ds_read_b128 v[206:209], v165 offset:3072
	ds_read_b128 v[210:213], v165 offset:4096
	ds_read_b128 v[214:217], v165 offset:5120
	ds_read_b128 v[218:221], v165 offset:6144
	ds_read_b128 v[222:225], v165 offset:7168
	global_load_lds_dwordx4 v152, s[54:55]
	s_add_i32 m0, s9, 0xe000
	s_nop 0
	global_load_lds_dwordx4 v154, s[54:55]
	s_waitcnt vmcnt(8)
	s_waitcnt lgkmcnt(0)
	s_barrier
	s_setprio 1
	s_waitcnt lgkmcnt(0)
	v_mfma_f32_16x16x32_f16 v[142:145], v[32:35], v[194:197], 0
	v_mfma_f32_16x16x32_f16 v[138:141], v[40:43], v[194:197], 0
	v_mfma_f32_16x16x32_f16 v[124:127], v[32:35], v[202:205], 0
	v_mfma_f32_16x16x32_f16 v[120:123], v[40:43], v[202:205], 0
	v_mfma_f32_16x16x32_f16 v[108:111], v[32:35], v[210:213], 0
	v_mfma_f32_16x16x32_f16 v[104:107], v[40:43], v[210:213], 0
	v_mfma_f32_16x16x32_f16 v[92:95], v[32:35], v[218:221], 0
	v_mfma_f32_16x16x32_f16 v[88:91], v[40:43], v[218:221], 0
	v_mfma_f32_16x16x32_f16 v[142:145], v[36:39], v[198:201], v[142:145]
	v_mfma_f32_16x16x32_f16 v[138:141], v[44:47], v[198:201], v[138:141]
	v_mfma_f32_16x16x32_f16 v[124:127], v[36:39], v[206:209], v[124:127]
	v_mfma_f32_16x16x32_f16 v[120:123], v[44:47], v[206:209], v[120:123]
	v_mfma_f32_16x16x32_f16 v[108:111], v[36:39], v[214:217], v[108:111]
	v_mfma_f32_16x16x32_f16 v[104:107], v[44:47], v[214:217], v[104:107]
	v_mfma_f32_16x16x32_f16 v[92:95], v[36:39], v[222:225], v[92:95]
	v_mfma_f32_16x16x32_f16 v[88:91], v[44:47], v[222:225], v[88:91]
	v_mfma_f32_16x16x32_f16 v[134:137], v[156:159], v[194:197], 0
	v_mfma_f32_16x16x32_f16 v[130:133], v[186:189], v[194:197], 0
	v_mfma_f32_16x16x32_f16 v[116:119], v[156:159], v[202:205], 0
	v_mfma_f32_16x16x32_f16 v[112:115], v[186:189], v[202:205], 0
	v_mfma_f32_16x16x32_f16 v[100:103], v[156:159], v[210:213], 0
	v_mfma_f32_16x16x32_f16 v[96:99], v[186:189], v[210:213], 0
	v_mfma_f32_16x16x32_f16 v[84:87], v[156:159], v[218:221], 0
	v_mfma_f32_16x16x32_f16 v[80:83], v[186:189], v[218:221], 0
	v_mfma_f32_16x16x32_f16 v[134:137], v[168:171], v[198:201], v[134:137]
	v_mfma_f32_16x16x32_f16 v[130:133], v[190:193], v[198:201], v[130:133]
	v_mfma_f32_16x16x32_f16 v[116:119], v[168:171], v[206:209], v[116:119]
	v_mfma_f32_16x16x32_f16 v[112:115], v[190:193], v[206:209], v[112:115]
	v_mfma_f32_16x16x32_f16 v[100:103], v[168:171], v[214:217], v[100:103]
	v_mfma_f32_16x16x32_f16 v[96:99], v[190:193], v[214:217], v[96:99]
	v_mfma_f32_16x16x32_f16 v[84:87], v[168:171], v[222:225], v[84:87]
	v_mfma_f32_16x16x32_f16 v[80:83], v[190:193], v[222:225], v[80:83]
	s_setprio 0
	s_barrier
	s_add_u32 s98, s56, s16
	s_addc_u32 s99, s57, s17
	s_add_u32 s100, s58, s16
	s_addc_u32 s101, s59, s17
	s_add_i32 s62, s62, s8
	s_mov_b32 m0, s62
	ds_read_b128 v[194:197], v165 offset:16384
	ds_read_b128 v[198:201], v165 offset:17408
	ds_read_b128 v[202:205], v165 offset:18432
	ds_read_b128 v[206:209], v165 offset:19456
	ds_read_b128 v[210:213], v165 offset:20480
	ds_read_b128 v[214:217], v165 offset:21504
	ds_read_b128 v[218:221], v165 offset:22528
	ds_read_b128 v[222:225], v165 offset:23552
	global_load_lds_dwordx4 v128, s[56:57]
	s_add_i32 m0, s62, 0x2000
	s_add_u32 s62, s56, 0x40000
	s_addc_u32 s63, s57, 0
	s_add_i32 s64, s64, s8
	global_load_lds_dwordx4 v146, s[56:57]
	s_mov_b32 m0, s64
	s_nop 0
	global_load_lds_dwordx4 v128, s[62:63]
	s_add_i32 m0, s64, 0x2000
	s_nop 0
	global_load_lds_dwordx4 v146, s[62:63]
	s_mov_b32 m0, s9
	s_nop 0
	global_load_lds_dwordx4 v150, s[58:59]
	s_mov_b32 m0, s10
	s_nop 0
	global_load_lds_dwordx4 v148, s[58:59]
	s_waitcnt vmcnt(8)
	s_waitcnt lgkmcnt(0)
	s_barrier
; #define PG8_STAGE(bufoff, gbase, voff) do { _Pragma("unroll") for (int _i = 0; _i < 2; ++_i) \
;         __builtin_amdgcn_global_load_lds((const unsigned*)((const char*)(gbase) + (voff)[_i]), (PG8_LAS unsigned*)(lds + (bufoff) + ldsw + _i * 8192), 16, 0, 0); } while (0)
; #define PG8_LDA(dst, b, h) do { _Pragma("unroll") for (int m = 0; m < 4; ++m) _Pragma("unroll") for (int k = 0; k < 2; ++k) dst[m][k] = *(const PG8_LAS bf16x8*)(lds + PG8_SA(b, h) + aoff + m * 2048 + k * 1024); } while (0)
; #define PG8_LDB(dst, b, h) do { _Pragma("unroll") for (int n = 0; n < 2; ++n) _Pragma("unroll") for (int k = 0; k < 2; ++k) dst[n][k] = *(const PG8_LAS bf16x8*)(lds + PG8_SB(b, h) + boff + n * 2048 + k * 1024); } while (0)
; #define PG8_MMA(ai, bj, At, Bt) do { __builtin_amdgcn_s_setprio(1); _Pragma("unroll") for (int m = 0; m < 4; ++m) _Pragma("unroll") for (int n = 0; n < 2; ++n) _Pragma("unroll") for (int k = 0; k < 2; ++k) \
;         acc[ai][bj][m][n] = mma16<F16>(Bt[n][k], At[m][k], acc[ai][bj][m][n]); __builtin_amdgcn_s_setprio(0); } while (0)
; #define PG8_WAIT_V(n) asm volatile("s_waitcnt vmcnt(" #n ")" ::: "memory")
; #define PG8_WAIT_L(n) asm volatile("s_waitcnt lgkmcnt(" #n ")" ::: "memory")
; #define PG8_BAR __builtin_amdgcn_s_barrier()
; #define PG8_SCHED __builtin_amdgcn_sched_barrier(0)
; template <class Epi, class Sched, bool ALIGN_EPI = false, bool SP2 = false, bool F16 = false>
; __device__ __forceinline__ void gemm_phase(PG8_LAS unsigned char* lds, const Gemm g, const Sched& S, const Epi& E) {
;     ...
;             PG8_WAIT_V(8); PG8_WAIT_L(0); PG8_BAR; PG8_MMA(1, 0, At, B0); PG8_MMA(1, 1, At, B1); PG8_BAR; PG8_SCHED;
;             PG8_LDB(B0, 1, 0); PG8_LDB(B1, 1, 1); PG8_SCHED; PG8_LDA(At, 1, 0); PG8_STAGE(PG8_SA(0, 1), a2 + hstep, voffA);
;             PG8_WAIT_V(8); PG8_WAIT_L(0); PG8_BAR; PG8_MMA(0, 0, At, B0); PG8_MMA(0, 1, At, B1); PG8_BAR; PG8_SCHED;
;             PG8_LDA(At, 1, 1); PG8_STAGE(PG8_SB(1, 0), b3, voffB); PG8_STAGE(PG8_SB(1, 1), b3 + hstep, voffB); PG8_STAGE(PG8_SA(1, 0), a3, voffA);
	s_setprio 1
	s_waitcnt lgkmcnt(0)
	v_mfma_f32_16x16x32_f16 v[76:79], v[32:35], v[194:197], 0
	v_mfma_f32_16x16x32_f16 v[72:75], v[40:43], v[194:197], 0
	v_mfma_f32_16x16x32_f16 v[60:63], v[32:35], v[202:205], 0
	v_mfma_f32_16x16x32_f16 v[56:59], v[40:43], v[202:205], 0
	v_mfma_f32_16x16x32_f16 v[28:31], v[32:35], v[210:213], 0
	v_mfma_f32_16x16x32_f16 v[24:27], v[40:43], v[210:213], 0
	v_mfma_f32_16x16x32_f16 v[12:15], v[32:35], v[218:221], 0
	v_mfma_f32_16x16x32_f16 v[8:11], v[40:43], v[218:221], 0
	v_mfma_f32_16x16x32_f16 v[76:79], v[36:39], v[198:201], v[76:79]
	v_mfma_f32_16x16x32_f16 v[72:75], v[44:47], v[198:201], v[72:75]
	v_mfma_f32_16x16x32_f16 v[60:63], v[36:39], v[206:209], v[60:63]
	v_mfma_f32_16x16x32_f16 v[56:59], v[44:47], v[206:209], v[56:59]
	v_mfma_f32_16x16x32_f16 v[28:31], v[36:39], v[214:217], v[28:31]
	v_mfma_f32_16x16x32_f16 v[24:27], v[44:47], v[214:217], v[24:27]
	v_mfma_f32_16x16x32_f16 v[12:15], v[36:39], v[222:225], v[12:15]
	v_mfma_f32_16x16x32_f16 v[8:11], v[44:47], v[222:225], v[8:11]
	v_mfma_f32_16x16x32_f16 v[20:23], v[156:159], v[210:213], 0
	v_mfma_f32_16x16x32_f16 v[16:19], v[186:189], v[210:213], 0
	v_mfma_f32_16x16x32_f16 v[4:7], v[156:159], v[218:221], 0
	v_mfma_f32_16x16x32_f16 v[0:3], v[186:189], v[218:221], 0
	v_mfma_f32_16x16x32_f16 v[32:35], v[156:159], v[194:197], 0
	v_mfma_f32_16x16x32_f16 v[36:39], v[186:189], v[194:197], 0
	v_mfma_f32_16x16x32_f16 v[40:43], v[156:159], v[202:205], 0
	v_mfma_f32_16x16x32_f16 v[44:47], v[186:189], v[202:205], 0
	v_mfma_f32_16x16x32_f16 v[20:23], v[168:171], v[214:217], v[20:23]
	v_mfma_f32_16x16x32_f16 v[16:19], v[190:193], v[214:217], v[16:19]
	v_mfma_f32_16x16x32_f16 v[4:7], v[168:171], v[222:225], v[4:7]
	v_mfma_f32_16x16x32_f16 v[0:3], v[190:193], v[222:225], v[0:3]
	v_mfma_f32_16x16x32_f16 v[32:35], v[168:171], v[198:201], v[32:35]
	v_mfma_f32_16x16x32_f16 v[36:39], v[190:193], v[198:201], v[36:39]
	v_mfma_f32_16x16x32_f16 v[40:43], v[168:171], v[206:209], v[40:43]
	v_mfma_f32_16x16x32_f16 v[44:47], v[190:193], v[206:209], v[44:47]
	s_setprio 0
	s_barrier
	s_add_i32 s62, 0, 0x18000
	s_add_i32 s63, 0, 0x1c000
	ds_read_b128 v[48:51], v172 offset:32768
	ds_read_b128 v[52:55], v172 offset:33792
	ds_read_b128 v[64:67], v172 offset:34816
	ds_read_b128 v[68:71], v172 offset:35840
	ds_read_b128 v[156:159], v172 offset:49152
	ds_read_b128 v[168:171], v172 offset:50176
	ds_read_b128 v[186:189], v172 offset:51200
	ds_read_b128 v[190:193], v172 offset:52224
	s_add_u32 s58, s58, 0x40000
	s_addc_u32 s59, s59, 0
	s_mov_b32 m0, s11
	ds_read_b128 v[194:197], v165 offset:32768
	ds_read_b128 v[198:201], v165 offset:33792
	ds_read_b128 v[202:205], v165 offset:34816
	ds_read_b128 v[206:209], v165 offset:35840
	ds_read_b128 v[210:213], v165 offset:36864
	ds_read_b128 v[214:217], v165 offset:37888
	ds_read_b128 v[218:221], v165 offset:38912
	ds_read_b128 v[222:225], v165 offset:39936
	global_load_lds_dwordx4 v150, s[58:59]
	s_mov_b32 m0, s13
	s_nop 0
	global_load_lds_dwordx4 v148, s[58:59]
	s_waitcnt vmcnt(8)
	s_waitcnt lgkmcnt(0)
	s_barrier
	s_setprio 1
	s_waitcnt lgkmcnt(0)
	v_mfma_f32_16x16x32_f16 v[142:145], v[48:51], v[194:197], v[142:145]
	v_mfma_f32_16x16x32_f16 v[138:141], v[64:67], v[194:197], v[138:141]
	v_mfma_f32_16x16x32_f16 v[124:127], v[48:51], v[202:205], v[124:127]
	v_mfma_f32_16x16x32_f16 v[120:123], v[64:67], v[202:205], v[120:123]
	v_mfma_f32_16x16x32_f16 v[108:111], v[48:51], v[210:213], v[108:111]
	v_mfma_f32_16x16x32_f16 v[104:107], v[64:67], v[210:213], v[104:107]
	v_mfma_f32_16x16x32_f16 v[92:95], v[48:51], v[218:221], v[92:95]
	v_mfma_f32_16x16x32_f16 v[88:91], v[64:67], v[218:221], v[88:91]
	v_mfma_f32_16x16x32_f16 v[142:145], v[52:55], v[198:201], v[142:145]
	v_mfma_f32_16x16x32_f16 v[138:141], v[68:71], v[198:201], v[138:141]
	v_mfma_f32_16x16x32_f16 v[124:127], v[52:55], v[206:209], v[124:127]
	v_mfma_f32_16x16x32_f16 v[120:123], v[68:71], v[206:209], v[120:123]
	v_mfma_f32_16x16x32_f16 v[108:111], v[52:55], v[214:217], v[108:111]
	v_mfma_f32_16x16x32_f16 v[104:107], v[68:71], v[214:217], v[104:107]
	v_mfma_f32_16x16x32_f16 v[92:95], v[52:55], v[222:225], v[92:95]
	v_mfma_f32_16x16x32_f16 v[88:91], v[68:71], v[222:225], v[88:91]
	v_mfma_f32_16x16x32_f16 v[134:137], v[156:159], v[194:197], v[134:137]
	v_mfma_f32_16x16x32_f16 v[130:133], v[186:189], v[194:197], v[130:133]
	v_mfma_f32_16x16x32_f16 v[116:119], v[156:159], v[202:205], v[116:119]
	v_mfma_f32_16x16x32_f16 v[112:115], v[186:189], v[202:205], v[112:115]
	v_mfma_f32_16x16x32_f16 v[100:103], v[156:159], v[210:213], v[100:103]
	v_mfma_f32_16x16x32_f16 v[96:99], v[186:189], v[210:213], v[96:99]
	v_mfma_f32_16x16x32_f16 v[84:87], v[156:159], v[218:221], v[84:87]
	v_mfma_f32_16x16x32_f16 v[80:83], v[186:189], v[218:221], v[80:83]
	v_mfma_f32_16x16x32_f16 v[134:137], v[168:171], v[198:201], v[134:137]
	v_mfma_f32_16x16x32_f16 v[130:133], v[190:193], v[198:201], v[130:133]
	v_mfma_f32_16x16x32_f16 v[116:119], v[168:171], v[206:209], v[116:119]
	v_mfma_f32_16x16x32_f16 v[112:115], v[190:193], v[206:209], v[112:115]
	v_mfma_f32_16x16x32_f16 v[100:103], v[168:171], v[214:217], v[100:103]
	v_mfma_f32_16x16x32_f16 v[96:99], v[190:193], v[214:217], v[96:99]
	v_mfma_f32_16x16x32_f16 v[84:87], v[168:171], v[222:225], v[84:87]
	v_mfma_f32_16x16x32_f16 v[80:83], v[190:193], v[222:225], v[80:83]
	s_setprio 0
	s_barrier
; #define PG8_STAGE(bufoff, gbase, voff) do { _Pragma("unroll") for (int _i = 0; _i < 2; ++_i) \
;         __builtin_amdgcn_global_load_lds((const unsigned*)((const char*)(gbase) + (voff)[_i]), (PG8_LAS unsigned*)(lds + (bufoff) + ldsw + _i * 8192), 16, 0, 0); } while (0)
; #define PG8_LDA(dst, b, h) do { _Pragma("unroll") for (int m = 0; m < 4; ++m) _Pragma("unroll") for (int k = 0; k < 2; ++k) dst[m][k] = *(const PG8_LAS bf16x8*)(lds + PG8_SA(b, h) + aoff + m * 2048 + k * 1024); } while (0)
; #define PG8_MMA(ai, bj, At, Bt) do { __builtin_amdgcn_s_setprio(1); _Pragma("unroll") for (int m = 0; m < 4; ++m) _Pragma("unroll") for (int n = 0; n < 2; ++n) _Pragma("unroll") for (int k = 0; k < 2; ++k) \
;         acc[ai][bj][m][n] = mma16<F16>(Bt[n][k], At[m][k], acc[ai][bj][m][n]); __builtin_amdgcn_s_setprio(0); } while (0)
; #define PG8_WAIT_V(n) asm volatile("s_waitcnt vmcnt(" #n ")" ::: "memory")
; #define PG8_WAIT_L(n) asm volatile("s_waitcnt lgkmcnt(" #n ")" ::: "memory")
; #define PG8_BAR __builtin_amdgcn_s_barrier()
; #define PG8_SCHED __builtin_amdgcn_sched_barrier(0)
; template <class Epi, class Sched, bool ALIGN_EPI = false, bool SP2 = false, bool F16 = false>
; __device__ __forceinline__ void gemm_phase(PG8_LAS unsigned char* lds, const Gemm g, const Sched& S, const Epi& E) {
;     ...
;             PG8_LDA(At, 1, 1); PG8_STAGE(PG8_SB(1, 0), b3, voffB); PG8_STAGE(PG8_SB(1, 1), b3 + hstep, voffB); PG8_STAGE(PG8_SA(1, 0), a3, voffA);
;             PG8_WAIT_V(8); PG8_WAIT_L(0); PG8_BAR; PG8_MMA(1, 0, At, B0); PG8_MMA(1, 1, At, B1); PG8_BAR; PG8_SCHED;
	s_add_i32 s58, s62, s8
	s_mov_b32 m0, s58
	ds_read_b128 v[194:197], v165 offset:49152
	ds_read_b128 v[198:201], v165 offset:50176
	ds_read_b128 v[202:205], v165 offset:51200
	ds_read_b128 v[206:209], v165 offset:52224
	ds_read_b128 v[210:213], v165 offset:53248
	ds_read_b128 v[214:217], v165 offset:54272
	ds_read_b128 v[218:221], v165 offset:55296
	ds_read_b128 v[222:225], v165 offset:56320
	global_load_lds_dwordx4 v128, s[98:99]
	s_add_i32 m0, s58, 0x2000
	s_add_u32 s56, s56, 0x40080
	s_addc_u32 s57, s57, 0
	s_add_i32 s58, s63, s8
	global_load_lds_dwordx4 v146, s[98:99]
	s_mov_b32 m0, s58
	s_nop 0
	global_load_lds_dwordx4 v128, s[56:57]
	s_add_i32 m0, s58, 0x2000
	s_nop 0
	global_load_lds_dwordx4 v146, s[56:57]
	s_mov_b32 m0, s20
	s_nop 0
	global_load_lds_dwordx4 v150, s[100:101]
	s_mov_b32 m0, s21
	s_nop 0
	global_load_lds_dwordx4 v148, s[100:101]
	s_waitcnt vmcnt(8)
	s_waitcnt lgkmcnt(0)
	s_barrier
	s_setprio 1
	s_waitcnt lgkmcnt(0)
	v_mfma_f32_16x16x32_f16 v[76:79], v[48:51], v[194:197], v[76:79]
	v_mfma_f32_16x16x32_f16 v[72:75], v[64:67], v[194:197], v[72:75]
	v_mfma_f32_16x16x32_f16 v[60:63], v[48:51], v[202:205], v[60:63]
	v_mfma_f32_16x16x32_f16 v[56:59], v[64:67], v[202:205], v[56:59]
	v_mfma_f32_16x16x32_f16 v[28:31], v[48:51], v[210:213], v[28:31]
	v_mfma_f32_16x16x32_f16 v[24:27], v[64:67], v[210:213], v[24:27]
	v_mfma_f32_16x16x32_f16 v[12:15], v[48:51], v[218:221], v[12:15]
	v_mfma_f32_16x16x32_f16 v[8:11], v[64:67], v[218:221], v[8:11]
	v_mfma_f32_16x16x32_f16 v[76:79], v[52:55], v[198:201], v[76:79]
	v_mfma_f32_16x16x32_f16 v[72:75], v[68:71], v[198:201], v[72:75]
	v_mfma_f32_16x16x32_f16 v[60:63], v[52:55], v[206:209], v[60:63]
	v_mfma_f32_16x16x32_f16 v[56:59], v[68:71], v[206:209], v[56:59]
	v_mfma_f32_16x16x32_f16 v[28:31], v[52:55], v[214:217], v[28:31]
	v_mfma_f32_16x16x32_f16 v[24:27], v[68:71], v[214:217], v[24:27]
	v_mfma_f32_16x16x32_f16 v[12:15], v[52:55], v[222:225], v[12:15]
	v_mfma_f32_16x16x32_f16 v[8:11], v[68:71], v[222:225], v[8:11]
	v_mfma_f32_16x16x32_f16 v[32:35], v[156:159], v[194:197], v[32:35]
	v_mfma_f32_16x16x32_f16 v[68:71], v[168:171], v[198:201], v[32:35]
	v_mfma_f32_16x16x32_f16 v[32:35], v[186:189], v[194:197], v[36:39]
	v_mfma_f32_16x16x32_f16 v[64:67], v[190:193], v[198:201], v[32:35]
	v_mfma_f32_16x16x32_f16 v[32:35], v[156:159], v[202:205], v[40:43]
	v_mfma_f32_16x16x32_f16 v[52:55], v[168:171], v[206:209], v[32:35]
	v_mfma_f32_16x16x32_f16 v[32:35], v[186:189], v[202:205], v[44:47]
	v_mfma_f32_16x16x32_f16 v[20:23], v[156:159], v[210:213], v[20:23]
	v_mfma_f32_16x16x32_f16 v[16:19], v[186:189], v[210:213], v[16:19]
	v_mfma_f32_16x16x32_f16 v[4:7], v[156:159], v[218:221], v[4:7]
	v_mfma_f32_16x16x32_f16 v[0:3], v[186:189], v[218:221], v[0:3]
	v_mfma_f32_16x16x32_f16 v[48:51], v[190:193], v[206:209], v[32:35]
	v_mfma_f32_16x16x32_f16 v[20:23], v[168:171], v[214:217], v[20:23]
	v_mfma_f32_16x16x32_f16 v[16:19], v[190:193], v[214:217], v[16:19]
	v_mfma_f32_16x16x32_f16 v[4:7], v[168:171], v[222:225], v[4:7]
	v_mfma_f32_16x16x32_f16 v[0:3], v[190:193], v[222:225], v[0:3]
	s_setprio 0
	s_barrier
	s_add_i32 s61, s61, 2
	s_add_u32 s54, s54, 0x100
	s_addc_u32 s55, s55, 0
	s_add_u32 s49, s49, 0x100
	s_addc_u32 s60, s60, 0
	s_cmp_gt_u32 s61, 13

; #define PG8_STAGE(bufoff, gbase, voff) do { _Pragma("unroll") for (int _i = 0; _i < 2; ++_i) \
;         __builtin_amdgcn_global_load_lds((const unsigned*)((const char*)(gbase) + (voff)[_i]), (PG8_LAS unsigned*)(lds + (bufoff) + ldsw + _i * 8192), 16, 0, 0); } while (0)
; #define PG8_LDA(dst, b, h) do { _Pragma("unroll") for (int m = 0; m < 4; ++m) _Pragma("unroll") for (int k = 0; k < 2; ++k) dst[m][k] = *(const PG8_LAS bf16x8*)(lds + PG8_SA(b, h) + aoff + m * 2048 + k * 1024); } while (0)
; #define PG8_LDB(dst, b, h) do { _Pragma("unroll") for (int n = 0; n < 2; ++n) _Pragma("unroll") for (int k = 0; k < 2; ++k) dst[n][k] = *(const PG8_LAS bf16x8*)(lds + PG8_SB(b, h) + boff + n * 2048 + k * 1024); } while (0)
; #define PG8_MMA(ai, bj, At, Bt) do { __builtin_amdgcn_s_setprio(1); _Pragma("unroll") for (int m = 0; m < 4; ++m) _Pragma("unroll") for (int n = 0; n < 2; ++n) _Pragma("unroll") for (int k = 0; k < 2; ++k) \
;         acc[ai][bj][m][n] = mma16<F16>(Bt[n][k], At[m][k], acc[ai][bj][m][n]); __builtin_amdgcn_s_setprio(0); } while (0)
; #define PG8_WAIT_V(n) asm volatile("s_waitcnt vmcnt(" #n ")" ::: "memory")
; #define PG8_WAIT_L(n) asm volatile("s_waitcnt lgkmcnt(" #n ")" ::: "memory")
; #define PG8_BAR __builtin_amdgcn_s_barrier()
; #define PG8_SCHED __builtin_amdgcn_sched_barrier(0)
; template <class Epi, class Sched, bool ALIGN_EPI = false, bool SP2 = false, bool F16 = false>
; __device__ __forceinline__ void gemm_phase(PG8_LAS unsigned char* lds, const Gemm g, const Sched& S, const Epi& E) {
;     ...
;             PG8_LDB(B0, 0, 0); PG8_LDB(B1, 0, 1); PG8_SCHED; PG8_LDA(At, 0, 0); PG8_STAGE(PG8_SA(1, 1), a1 + hstep, voffA);
;             PG8_WAIT_V(8); PG8_WAIT_L(0); PG8_BAR; PG8_MMA(0, 0, At, B0); PG8_MMA(0, 1, At, B1); PG8_BAR; PG8_SCHED;
;             PG8_LDA(At, 0, 1); PG8_STAGE(PG8_SB(0, 0), b2, voffB); PG8_STAGE(PG8_SB(0, 1), b2 + hstep, voffB); PG8_STAGE(PG8_SA(0, 0), a2, voffA);
;             PG8_WAIT_V(8); PG8_WAIT_L(0); PG8_BAR; PG8_MMA(1, 0, At, B0); PG8_MMA(1, 1, At, B1); PG8_BAR; PG8_SCHED;
;     ...
; #pragma unroll
;         for (int a = 0; a < 2; ++a)
; #pragma unroll
;             for (int b = 0; b < 2; ++b)
; #pragma unroll
;                 for (int m = 0; m < 4; ++m)
; #pragma unroll
;                     for (int n = 0; n < 2; ++n) acc[a][b][m][n] = (f32x4){0.f, 0.f, 0.f, 0.f};
.LBB0_996:
	s_add_u32 s4, s50, 0x100
	s_addc_u32 s5, s51, 0
	s_mov_b32 s58, -2
	s_waitcnt lgkmcnt(0)
	s_waitcnt vmcnt(0)
	v_add_u32_e32 v172, 0x10000, v224
	s_add_u32 s50, s48, 0x100
	s_addc_u32 s51, s49, 0
	s_add_i32 s59, 0, 0x10000
	s_cmp_eq_u32 s58, 40
	s_cselect_b32 s55, s43, s51
	s_cselect_b32 s54, s42, s50
	s_cselect_b32 s53, s47, s5
	s_cselect_b32 s52, s46, s4
	s_add_i32 s60, 0, 0x14000
	ds_read_b128 v[130:133], v172
	ds_read_b128 v[134:137], v172 offset:1024
	ds_read_b128 v[138:141], v172 offset:2048
	ds_read_b128 v[142:145], v172 offset:3072
	ds_read_b128 v[146:149], v172 offset:16384
	ds_read_b128 v[150:153], v172 offset:17408
	ds_read_b128 v[154:157], v172 offset:18432
	ds_read_b128 v[158:161], v172 offset:19456
	s_add_i32 m0, s9, 0xc000
	ds_read_b128 v[186:189], v225
	ds_read_b128 v[190:193], v225 offset:1024
	ds_read_b128 v[194:197], v225 offset:2048
	ds_read_b128 v[198:201], v225 offset:3072
	ds_read_b128 v[202:205], v225 offset:4096
	ds_read_b128 v[206:209], v225 offset:5120
	ds_read_b128 v[210:213], v225 offset:6144
	ds_read_b128 v[214:217], v225 offset:7168
	global_load_lds_dwordx4 v168, s[48:49]
	s_add_i32 m0, s9, 0xe000
	s_nop 0
	global_load_lds_dwordx4 v170, s[48:49]
	s_waitcnt vmcnt(8)
	s_waitcnt lgkmcnt(0)
	s_barrier
	s_setprio 1
	s_waitcnt lgkmcnt(0)
	v_mfma_f32_16x16x32_bf16 v[124:127], v[130:133], v[186:189], 0
	v_mfma_f32_16x16x32_bf16 v[120:123], v[138:141], v[186:189], 0
	v_mfma_f32_16x16x32_bf16 v[116:119], v[130:133], v[194:197], 0
	v_mfma_f32_16x16x32_bf16 v[112:115], v[138:141], v[194:197], 0
	v_mfma_f32_16x16x32_bf16 v[108:111], v[130:133], v[202:205], 0
	v_mfma_f32_16x16x32_bf16 v[104:107], v[138:141], v[202:205], 0
	v_mfma_f32_16x16x32_bf16 v[100:103], v[130:133], v[210:213], 0
	v_mfma_f32_16x16x32_bf16 v[96:99], v[138:141], v[210:213], 0
	v_mfma_f32_16x16x32_bf16 v[124:127], v[134:137], v[190:193], v[124:127]
	v_mfma_f32_16x16x32_bf16 v[120:123], v[142:145], v[190:193], v[120:123]
	v_mfma_f32_16x16x32_bf16 v[116:119], v[134:137], v[198:201], v[116:119]
	v_mfma_f32_16x16x32_bf16 v[112:115], v[142:145], v[198:201], v[112:115]
	v_mfma_f32_16x16x32_bf16 v[108:111], v[134:137], v[206:209], v[108:111]
	v_mfma_f32_16x16x32_bf16 v[104:107], v[142:145], v[206:209], v[104:107]
	v_mfma_f32_16x16x32_bf16 v[100:103], v[134:137], v[214:217], v[100:103]
	v_mfma_f32_16x16x32_bf16 v[96:99], v[142:145], v[214:217], v[96:99]
	v_mfma_f32_16x16x32_bf16 v[60:63], v[146:149], v[186:189], 0
	v_mfma_f32_16x16x32_bf16 v[56:59], v[154:157], v[186:189], 0
	v_mfma_f32_16x16x32_bf16 v[52:55], v[146:149], v[194:197], 0
	v_mfma_f32_16x16x32_bf16 v[48:51], v[154:157], v[194:197], 0
	v_mfma_f32_16x16x32_bf16 v[44:47], v[146:149], v[202:205], 0
	v_mfma_f32_16x16x32_bf16 v[40:43], v[154:157], v[202:205], 0
	v_mfma_f32_16x16x32_bf16 v[36:39], v[146:149], v[210:213], 0
	v_mfma_f32_16x16x32_bf16 v[32:35], v[154:157], v[210:213], 0
	v_mfma_f32_16x16x32_bf16 v[60:63], v[150:153], v[190:193], v[60:63]
	v_mfma_f32_16x16x32_bf16 v[56:59], v[158:161], v[190:193], v[56:59]
	v_mfma_f32_16x16x32_bf16 v[52:55], v[150:153], v[198:201], v[52:55]
	v_mfma_f32_16x16x32_bf16 v[48:51], v[158:161], v[198:201], v[48:51]
	v_mfma_f32_16x16x32_bf16 v[44:47], v[150:153], v[206:209], v[44:47]
	v_mfma_f32_16x16x32_bf16 v[40:43], v[158:161], v[206:209], v[40:43]
	v_mfma_f32_16x16x32_bf16 v[36:39], v[150:153], v[214:217], v[36:39]
	v_mfma_f32_16x16x32_bf16 v[32:35], v[158:161], v[214:217], v[32:35]
	s_setprio 0
	s_barrier
	s_add_u32 s98, s52, s16
	s_addc_u32 s99, s53, s17
	s_add_u32 s100, s54, s16
	s_addc_u32 s101, s55, s17
	s_add_i32 s48, s59, s8
	s_mov_b32 m0, s48
	ds_read_b128 v[186:189], v225 offset:16384
	ds_read_b128 v[190:193], v225 offset:17408
	ds_read_b128 v[194:197], v225 offset:18432
	ds_read_b128 v[198:201], v225 offset:19456
	ds_read_b128 v[202:205], v225 offset:20480
	ds_read_b128 v[206:209], v225 offset:21504
	ds_read_b128 v[210:213], v225 offset:22528
	ds_read_b128 v[214:217], v225 offset:23552
	global_load_lds_dwordx4 v128, s[52:53]
	s_add_i32 m0, s48, 0x2000
	s_add_u32 s48, s52, 0xb0000
	s_addc_u32 s49, s53, 0
	s_add_i32 s59, s60, s8
	global_load_lds_dwordx4 v162, s[52:53]
	s_mov_b32 m0, s59
	s_nop 0
	global_load_lds_dwordx4 v128, s[48:49]
	s_add_i32 m0, s59, 0x2000
	s_nop 0
	global_load_lds_dwordx4 v162, s[48:49]
	s_mov_b32 m0, s9
	s_nop 0
	global_load_lds_dwordx4 v166, s[54:55]
	s_mov_b32 m0, s10
	s_nop 0
	global_load_lds_dwordx4 v164, s[54:55]
	s_waitcnt vmcnt(8)
	s_waitcnt lgkmcnt(0)
	s_barrier
	s_setprio 1
	s_waitcnt lgkmcnt(0)
	v_mfma_f32_16x16x32_bf16 v[92:95], v[130:133], v[186:189], 0
	v_mfma_f32_16x16x32_bf16 v[88:91], v[138:141], v[186:189], 0
	v_mfma_f32_16x16x32_bf16 v[84:87], v[130:133], v[194:197], 0
	v_mfma_f32_16x16x32_bf16 v[80:83], v[138:141], v[194:197], 0
	v_mfma_f32_16x16x32_bf16 v[76:79], v[130:133], v[202:205], 0
	v_mfma_f32_16x16x32_bf16 v[72:75], v[138:141], v[202:205], 0
	v_mfma_f32_16x16x32_bf16 v[68:71], v[130:133], v[210:213], 0
	v_mfma_f32_16x16x32_bf16 v[64:67], v[138:141], v[210:213], 0
	v_mfma_f32_16x16x32_bf16 v[92:95], v[134:137], v[190:193], v[92:95]
	v_mfma_f32_16x16x32_bf16 v[88:91], v[142:145], v[190:193], v[88:91]
	v_mfma_f32_16x16x32_bf16 v[84:87], v[134:137], v[198:201], v[84:87]
	v_mfma_f32_16x16x32_bf16 v[80:83], v[142:145], v[198:201], v[80:83]
	v_mfma_f32_16x16x32_bf16 v[76:79], v[134:137], v[206:209], v[76:79]
	v_mfma_f32_16x16x32_bf16 v[72:75], v[142:145], v[206:209], v[72:75]
	v_mfma_f32_16x16x32_bf16 v[68:71], v[134:137], v[214:217], v[68:71]
	v_mfma_f32_16x16x32_bf16 v[64:67], v[142:145], v[214:217], v[64:67]
	v_mfma_f32_16x16x32_bf16 v[28:31], v[146:149], v[186:189], 0
	v_mfma_f32_16x16x32_bf16 v[24:27], v[154:157], v[186:189], 0
	v_mfma_f32_16x16x32_bf16 v[20:23], v[146:149], v[194:197], 0
	v_mfma_f32_16x16x32_bf16 v[16:19], v[154:157], v[194:197], 0
	v_mfma_f32_16x16x32_bf16 v[12:15], v[146:149], v[202:205], 0
	v_mfma_f32_16x16x32_bf16 v[8:11], v[154:157], v[202:205], 0
	v_mfma_f32_16x16x32_bf16 v[4:7], v[146:149], v[210:213], 0
	v_mfma_f32_16x16x32_bf16 v[0:3], v[154:157], v[210:213], 0
	v_mfma_f32_16x16x32_bf16 v[28:31], v[150:153], v[190:193], v[28:31]
	v_mfma_f32_16x16x32_bf16 v[24:27], v[158:161], v[190:193], v[24:27]
	v_mfma_f32_16x16x32_bf16 v[20:23], v[150:153], v[198:201], v[20:23]
	v_mfma_f32_16x16x32_bf16 v[16:19], v[158:161], v[198:201], v[16:19]
	v_mfma_f32_16x16x32_bf16 v[12:15], v[150:153], v[206:209], v[12:15]
	v_mfma_f32_16x16x32_bf16 v[8:11], v[158:161], v[206:209], v[8:11]
	v_mfma_f32_16x16x32_bf16 v[4:7], v[150:153], v[214:217], v[4:7]
	v_mfma_f32_16x16x32_bf16 v[0:3], v[158:161], v[214:217], v[0:3]
	s_setprio 0
	s_barrier
; #define PG8_STAGE(bufoff, gbase, voff) do { _Pragma("unroll") for (int _i = 0; _i < 2; ++_i) \
;         __builtin_amdgcn_global_load_lds((const unsigned*)((const char*)(gbase) + (voff)[_i]), (PG8_LAS unsigned*)(lds + (bufoff) + ldsw + _i * 8192), 16, 0, 0); } while (0)
; #define PG8_LDA(dst, b, h) do { _Pragma("unroll") for (int m = 0; m < 4; ++m) _Pragma("unroll") for (int k = 0; k < 2; ++k) dst[m][k] = *(const PG8_LAS bf16x8*)(lds + PG8_SA(b, h) + aoff + m * 2048 + k * 1024); } while (0)
; #define PG8_LDB(dst, b, h) do { _Pragma("unroll") for (int n = 0; n < 2; ++n) _Pragma("unroll") for (int k = 0; k < 2; ++k) dst[n][k] = *(const PG8_LAS bf16x8*)(lds + PG8_SB(b, h) + boff + n * 2048 + k * 1024); } while (0)
; #define PG8_MMA(ai, bj, At, Bt) do { __builtin_amdgcn_s_setprio(1); _Pragma("unroll") for (int m = 0; m < 4; ++m) _Pragma("unroll") for (int n = 0; n < 2; ++n) _Pragma("unroll") for (int k = 0; k < 2; ++k) \
;         acc[ai][bj][m][n] = mma16<F16>(Bt[n][k], At[m][k], acc[ai][bj][m][n]); __builtin_amdgcn_s_setprio(0); } while (0)
; #define PG8_WAIT_V(n) asm volatile("s_waitcnt vmcnt(" #n ")" ::: "memory")
; #define PG8_WAIT_L(n) asm volatile("s_waitcnt lgkmcnt(" #n ")" ::: "memory")
; #define PG8_BAR __builtin_amdgcn_s_barrier()
; #define PG8_SCHED __builtin_amdgcn_sched_barrier(0)
; template <class Epi, class Sched, bool ALIGN_EPI = false, bool SP2 = false, bool F16 = false>
; __device__ __forceinline__ void gemm_phase(PG8_LAS unsigned char* lds, const Gemm g, const Sched& S, const Epi& E) {
;     ...
;             PG8_LDB(B0, 1, 0); PG8_LDB(B1, 1, 1); PG8_SCHED; PG8_LDA(At, 1, 0); PG8_STAGE(PG8_SA(0, 1), a2 + hstep, voffA);
;             PG8_WAIT_V(8); PG8_WAIT_L(0); PG8_BAR; PG8_MMA(0, 0, At, B0); PG8_MMA(0, 1, At, B1); PG8_BAR; PG8_SCHED;
;             PG8_LDA(At, 1, 1); PG8_STAGE(PG8_SB(1, 0), b3, voffB); PG8_STAGE(PG8_SB(1, 1), b3 + hstep, voffB); PG8_STAGE(PG8_SA(1, 0), a3, voffA);
;             PG8_WAIT_V(8); PG8_WAIT_L(0); PG8_BAR; PG8_MMA(1, 0, At, B0); PG8_MMA(1, 1, At, B1); PG8_BAR; PG8_SCHED;
	s_add_i32 s59, 0, 0x18000
	s_add_i32 s60, 0, 0x1c000
	ds_read_b128 v[130:133], v172 offset:32768
	ds_read_b128 v[134:137], v172 offset:33792
	ds_read_b128 v[138:141], v172 offset:34816
	ds_read_b128 v[142:145], v172 offset:35840
	ds_read_b128 v[146:149], v172 offset:49152
	ds_read_b128 v[150:153], v172 offset:50176
	ds_read_b128 v[154:157], v172 offset:51200
	ds_read_b128 v[158:161], v172 offset:52224
	s_add_u32 s48, s54, 0xb0000
	s_addc_u32 s49, s55, 0
	s_mov_b32 m0, s11
	ds_read_b128 v[186:189], v225 offset:32768
	ds_read_b128 v[190:193], v225 offset:33792
	ds_read_b128 v[194:197], v225 offset:34816
	ds_read_b128 v[198:201], v225 offset:35840
	ds_read_b128 v[202:205], v225 offset:36864
	ds_read_b128 v[206:209], v225 offset:37888
	ds_read_b128 v[210:213], v225 offset:38912
	ds_read_b128 v[214:217], v225 offset:39936
	global_load_lds_dwordx4 v166, s[48:49]
	s_mov_b32 m0, s14
	s_nop 0
	global_load_lds_dwordx4 v164, s[48:49]
	s_waitcnt vmcnt(8)
	s_waitcnt lgkmcnt(0)
	s_barrier
	s_setprio 1
	s_waitcnt lgkmcnt(0)
	v_mfma_f32_16x16x32_bf16 v[124:127], v[130:133], v[186:189], v[124:127]
	v_mfma_f32_16x16x32_bf16 v[120:123], v[138:141], v[186:189], v[120:123]
	v_mfma_f32_16x16x32_bf16 v[116:119], v[130:133], v[194:197], v[116:119]
	v_mfma_f32_16x16x32_bf16 v[112:115], v[138:141], v[194:197], v[112:115]
	v_mfma_f32_16x16x32_bf16 v[108:111], v[130:133], v[202:205], v[108:111]
	v_mfma_f32_16x16x32_bf16 v[104:107], v[138:141], v[202:205], v[104:107]
	v_mfma_f32_16x16x32_bf16 v[100:103], v[130:133], v[210:213], v[100:103]
	v_mfma_f32_16x16x32_bf16 v[96:99], v[138:141], v[210:213], v[96:99]
	v_mfma_f32_16x16x32_bf16 v[124:127], v[134:137], v[190:193], v[124:127]
	v_mfma_f32_16x16x32_bf16 v[120:123], v[142:145], v[190:193], v[120:123]
	v_mfma_f32_16x16x32_bf16 v[116:119], v[134:137], v[198:201], v[116:119]
	v_mfma_f32_16x16x32_bf16 v[112:115], v[142:145], v[198:201], v[112:115]
	v_mfma_f32_16x16x32_bf16 v[108:111], v[134:137], v[206:209], v[108:111]
	v_mfma_f32_16x16x32_bf16 v[104:107], v[142:145], v[206:209], v[104:107]
	v_mfma_f32_16x16x32_bf16 v[100:103], v[134:137], v[214:217], v[100:103]
	v_mfma_f32_16x16x32_bf16 v[96:99], v[142:145], v[214:217], v[96:99]
	v_mfma_f32_16x16x32_bf16 v[60:63], v[146:149], v[186:189], v[60:63]
	v_mfma_f32_16x16x32_bf16 v[56:59], v[154:157], v[186:189], v[56:59]
	v_mfma_f32_16x16x32_bf16 v[52:55], v[146:149], v[194:197], v[52:55]
	v_mfma_f32_16x16x32_bf16 v[48:51], v[154:157], v[194:197], v[48:51]
	v_mfma_f32_16x16x32_bf16 v[44:47], v[146:149], v[202:205], v[44:47]
	v_mfma_f32_16x16x32_bf16 v[40:43], v[154:157], v[202:205], v[40:43]
	v_mfma_f32_16x16x32_bf16 v[36:39], v[146:149], v[210:213], v[36:39]
	v_mfma_f32_16x16x32_bf16 v[32:35], v[154:157], v[210:213], v[32:35]
	v_mfma_f32_16x16x32_bf16 v[60:63], v[150:153], v[190:193], v[60:63]
	v_mfma_f32_16x16x32_bf16 v[56:59], v[158:161], v[190:193], v[56:59]
	v_mfma_f32_16x16x32_bf16 v[52:55], v[150:153], v[198:201], v[52:55]
	v_mfma_f32_16x16x32_bf16 v[48:51], v[158:161], v[198:201], v[48:51]
	v_mfma_f32_16x16x32_bf16 v[44:47], v[150:153], v[206:209], v[44:47]
	v_mfma_f32_16x16x32_bf16 v[40:43], v[158:161], v[206:209], v[40:43]
	v_mfma_f32_16x16x32_bf16 v[36:39], v[150:153], v[214:217], v[36:39]
	v_mfma_f32_16x16x32_bf16 v[32:35], v[158:161], v[214:217], v[32:35]
	s_setprio 0
	s_barrier
	s_add_i32 s48, s59, s8
	s_mov_b32 m0, s48
	ds_read_b128 v[186:189], v225 offset:49152
	ds_read_b128 v[190:193], v225 offset:50176
	ds_read_b128 v[194:197], v225 offset:51200
	ds_read_b128 v[198:201], v225 offset:52224
	ds_read_b128 v[202:205], v225 offset:53248
	ds_read_b128 v[206:209], v225 offset:54272
	ds_read_b128 v[210:213], v225 offset:55296
	ds_read_b128 v[214:217], v225 offset:56320
	global_load_lds_dwordx4 v128, s[98:99]
	s_add_i32 m0, s48, 0x2000
	s_add_u32 s48, s52, 0xb0080
	s_addc_u32 s49, s53, 0
	s_add_i32 s52, s60, s8
	global_load_lds_dwordx4 v162, s[98:99]
	s_mov_b32 m0, s52
	s_nop 0
	global_load_lds_dwordx4 v128, s[48:49]
	s_add_i32 m0, s52, 0x2000
	s_nop 0
	global_load_lds_dwordx4 v162, s[48:49]
	s_mov_b32 m0, s29
	s_nop 0
	global_load_lds_dwordx4 v166, s[100:101]
	s_mov_b32 m0, s30
	s_nop 0
	global_load_lds_dwordx4 v164, s[100:101]
	s_waitcnt vmcnt(8)
	s_waitcnt lgkmcnt(0)
	s_barrier
	s_setprio 1
	s_waitcnt lgkmcnt(0)
	v_mfma_f32_16x16x32_bf16 v[92:95], v[130:133], v[186:189], v[92:95]
	v_mfma_f32_16x16x32_bf16 v[88:91], v[138:141], v[186:189], v[88:91]
	v_mfma_f32_16x16x32_bf16 v[84:87], v[130:133], v[194:197], v[84:87]
	v_mfma_f32_16x16x32_bf16 v[80:83], v[138:141], v[194:197], v[80:83]
	v_mfma_f32_16x16x32_bf16 v[76:79], v[130:133], v[202:205], v[76:79]
	v_mfma_f32_16x16x32_bf16 v[72:75], v[138:141], v[202:205], v[72:75]
	v_mfma_f32_16x16x32_bf16 v[68:71], v[130:133], v[210:213], v[68:71]
	v_mfma_f32_16x16x32_bf16 v[64:67], v[138:141], v[210:213], v[64:67]
	v_mfma_f32_16x16x32_bf16 v[92:95], v[134:137], v[190:193], v[92:95]
	v_mfma_f32_16x16x32_bf16 v[88:91], v[142:145], v[190:193], v[88:91]
	v_mfma_f32_16x16x32_bf16 v[84:87], v[134:137], v[198:201], v[84:87]
	v_mfma_f32_16x16x32_bf16 v[80:83], v[142:145], v[198:201], v[80:83]
	v_mfma_f32_16x16x32_bf16 v[76:79], v[134:137], v[206:209], v[76:79]
	v_mfma_f32_16x16x32_bf16 v[72:75], v[142:145], v[206:209], v[72:75]
	v_mfma_f32_16x16x32_bf16 v[68:71], v[134:137], v[214:217], v[68:71]
	v_mfma_f32_16x16x32_bf16 v[64:67], v[142:145], v[214:217], v[64:67]
	v_mfma_f32_16x16x32_bf16 v[28:31], v[146:149], v[186:189], v[28:31]
	v_mfma_f32_16x16x32_bf16 v[24:27], v[154:157], v[186:189], v[24:27]
	v_mfma_f32_16x16x32_bf16 v[20:23], v[146:149], v[194:197], v[20:23]
	v_mfma_f32_16x16x32_bf16 v[16:19], v[154:157], v[194:197], v[16:19]
	v_mfma_f32_16x16x32_bf16 v[12:15], v[146:149], v[202:205], v[12:15]
	v_mfma_f32_16x16x32_bf16 v[8:11], v[154:157], v[202:205], v[8:11]
	v_mfma_f32_16x16x32_bf16 v[4:7], v[146:149], v[210:213], v[4:7]
	v_mfma_f32_16x16x32_bf16 v[0:3], v[154:157], v[210:213], v[0:3]
	v_mfma_f32_16x16x32_bf16 v[28:31], v[150:153], v[190:193], v[28:31]
	v_mfma_f32_16x16x32_bf16 v[24:27], v[158:161], v[190:193], v[24:27]
	v_mfma_f32_16x16x32_bf16 v[20:23], v[150:153], v[198:201], v[20:23]
	v_mfma_f32_16x16x32_bf16 v[16:19], v[158:161], v[198:201], v[16:19]
	v_mfma_f32_16x16x32_bf16 v[12:15], v[150:153], v[206:209], v[12:15]
	v_mfma_f32_16x16x32_bf16 v[8:11], v[158:161], v[206:209], v[8:11]
	v_mfma_f32_16x16x32_bf16 v[4:7], v[150:153], v[214:217], v[4:7]
	v_mfma_f32_16x16x32_bf16 v[0:3], v[158:161], v[214:217], v[0:3]
	s_setprio 0
	s_barrier
	s_add_i32 s58, s58, 2
	s_add_u32 s4, s4, 0x100
	s_addc_u32 s5, s5, 0
	s_cmp_gt_u32 s58, 41
	s_mov_b64 s[48:49], s[50:51]
